# hand-written residual epilogue also for out-proj C GEMM (Y += acc)
# speedup vs baseline: 1.4669x; 1.0207x over previous
.LBB0_2391:
	s_ashr_i32 s0, s6, 31
	v_readlane_b32 s1, v250, 22
	s_xor_b32 s0, s0, s1
	s_abs_i32 s1, s6
	v_readlane_b32 s2, v250, 26
	s_mul_hi_u32 s2, s1, s2
	v_readlane_b32 s5, v250, 20
	s_mul_i32 s3, s2, s5
	s_sub_i32 s1, s1, s3
	s_add_i32 s3, s2, 1
	s_sub_i32 s4, s1, s5
	s_cmp_ge_u32 s1, s5
	s_cselect_b32 s2, s3, s2
	s_cselect_b32 s1, s4, s1
	s_add_i32 s3, s2, 1
	s_cmp_ge_u32 s1, s5
	s_cselect_b32 s1, s3, s2
	s_xor_b32 s1, s1, s0
	s_sub_i32 s0, s1, s0
	s_mov_b32 s2, s6
	s_lshl_b32 s0, s0, 3
	v_readlane_b32 s1, v250, 24
	v_writelane_b32 v252, s2, 42
	s_mul_i32 s1, s1, s0
	s_add_i32 s1, s6, s1
	v_writelane_b32 v252, s3, 43
	s_and_b32 s2, s6, 7
	s_or_b32 s0, s0, s2
	s_lshr_b32 s1, s1, 3
	s_lshl_b32 s4, s0, 7
	v_readlane_b32 s0, v252, 40
	s_add_i32 s1, s1, s0
	v_mov_b32_e32 v82, v218
	s_lshl_b32 s0, s1, 7
	v_readlane_b32 s2, v250, 17
	v_ashrrev_i32_e32 v3, 3, v82
	v_add_u32_e32 v0, s0, v3
	v_ashrrev_i32_e32 v1, 31, v0
	v_lshlrev_b64 v[0:1], 11, v[0:1]
	v_readlane_b32 s3, v250, 18
	s_waitcnt vmcnt(2)
	v_lshlrev_b32_e32 v4, 4, v82
	v_and_b32_e32 v64, 0x70, v4
	v_lshl_add_u64 v[0:1], s[2:3], 0, v[0:1]
	v_lshl_add_u64 v[66:67], v[0:1], 0, v[64:65]
	v_add_u32_e32 v0, s4, v3
	v_ashrrev_i32_e32 v1, 31, v0
	v_readlane_b32 s2, v250, 15
	v_lshlrev_b64 v[0:1], 11, v[0:1]
	v_readlane_b32 s3, v250, 16
	s_mov_b32 s1, 0x10000
	v_add_co_u32_e32 v70, vcc, s1, v66
	v_lshl_add_u64 v[0:1], s[2:3], 0, v[0:1]
	v_lshl_add_u64 v[68:69], v[0:1], 0, v[64:65]
	v_lshrrev_b32_e32 v0, 4, v82
	v_addc_co_u32_e32 v71, vcc, 0, v67, vcc
	s_mov_b32 s2, 0x20000
	v_xor_b32_e32 v0, v0, v82
	v_ashrrev_i32_e32 v1, 1, v82
	v_add_co_u32_e32 v72, vcc, s2, v66
	v_and_b32_e32 v83, 31, v82
	v_lshlrev_b32_e32 v0, 4, v0
	v_and_b32_e32 v64, 0xffffffc0, v1
	v_addc_co_u32_e32 v73, vcc, 0, v67, vcc
	s_mov_b32 s3, 0x30000
	v_and_b32_e32 v0, 0x70, v0
	v_or_b32_e32 v1, v64, v83
	v_add_co_u32_e32 v74, vcc, s3, v66
	v_lshrrev_b32_e32 v2, 5, v82
	v_bfe_u32 v84, v82, 5, 1
	v_lshl_or_b32 v85, v3, 7, v0
	v_bfe_u32 v0, v82, 1, 3
	s_waitcnt vmcnt(0)
	v_lshlrev_b32_e32 v32, 7, v1
	v_lshlrev_b32_e32 v1, 7, v82
	v_addc_co_u32_e32 v75, vcc, 0, v67, vcc
	v_and_b32_e32 v33, 0x2f80, v1
	v_bitop3_b32 v34, v2, v0, 1 bitop3:0x6c
	v_bitop3_b32 v35, v84, v0, 2 bitop3:0x36
	v_bitop3_b32 v36, v84, v0, 4 bitop3:0x36
	v_bitop3_b32 v37, v84, v0, 6 bitop3:0x36
	global_load_dwordx4 v[0:3], v[66:67], off
	global_load_dwordx4 v[4:7], v[70:71], off
	global_load_dwordx4 v[8:11], v[72:73], off
	global_load_dwordx4 v[12:15], v[74:75], off
	global_load_dwordx4 v[16:19], v[68:69], off
	v_add_co_u32_e32 v76, vcc, s1, v68
	s_nop 1
	v_addc_co_u32_e32 v77, vcc, 0, v69, vcc
	v_add_co_u32_e32 v78, vcc, s2, v68
	global_load_dwordx4 v[20:23], v[76:77], off
	s_nop 0
	v_addc_co_u32_e32 v79, vcc, 0, v69, vcc
	global_load_dwordx4 v[24:27], v[78:79], off
	v_add_co_u32_e32 v80, vcc, s3, v68
	s_nop 1
	v_addc_co_u32_e32 v81, vcc, 0, v69, vcc
	global_load_dwordx4 v[28:31], v[80:81], off
	global_load_dwordx4 v[94:97], v[66:67], off offset:128
	global_load_dwordx4 v[98:101], v[70:71], off offset:128
	global_load_dwordx4 v[102:105], v[72:73], off offset:128
	global_load_dwordx4 v[106:109], v[74:75], off offset:128
	global_load_dwordx4 v[110:113], v[68:69], off offset:128
	global_load_dwordx4 v[114:117], v[76:77], off offset:128
	global_load_dwordx4 v[118:121], v[78:79], off offset:128
	global_load_dwordx4 v[122:125], v[80:81], off offset:128
	s_waitcnt vmcnt(15)
	ds_write_b128 v85, v[0:3]
	s_waitcnt vmcnt(14)
	ds_write_b128 v85, v[4:7] offset:4096
	s_waitcnt vmcnt(13)
	ds_write_b128 v85, v[8:11] offset:8192
	s_waitcnt vmcnt(12)
	ds_write_b128 v85, v[12:15] offset:12288
	s_waitcnt vmcnt(11)
	ds_write_b128 v85, v[16:19] offset:32768
	s_waitcnt vmcnt(10)
	ds_write_b128 v85, v[20:23] offset:36864
	s_waitcnt vmcnt(9)
	ds_write_b128 v85, v[24:27] offset:40960
	s_waitcnt vmcnt(8)
	ds_write_b128 v85, v[28:31] offset:45056
	s_waitcnt lgkmcnt(0)
	s_barrier
	global_load_dwordx4 v[126:129], v[66:67], off offset:256
	global_load_dwordx4 v[130:133], v[70:71], off offset:256
	global_load_dwordx4 v[136:139], v[72:73], off offset:256
	global_load_dwordx4 v[140:143], v[74:75], off offset:256
	global_load_dwordx4 v[144:147], v[68:69], off offset:256
	global_load_dwordx4 v[150:153], v[76:77], off offset:256
	global_load_dwordx4 v[154:157], v[78:79], off offset:256
	global_load_dwordx4 v[158:161], v[80:81], off offset:256
	v_lshlrev_b32_e32 v0, 4, v34
	v_or_b32_e32 v92, v32, v0
	v_or_b32_e32 v93, v33, v0
	v_lshlrev_b32_e32 v0, 4, v35
	v_or_b32_e32 v90, v32, v0
	v_or_b32_e32 v91, v33, v0
	v_lshlrev_b32_e32 v0, 4, v36
	v_or_b32_e32 v88, v32, v0
	v_or_b32_e32 v89, v33, v0
	v_lshlrev_b32_e32 v0, 4, v37
	v_or_b32_e32 v86, v32, v0
	v_or_b32_e32 v87, v33, v0
	ds_read_b128 v[0:3], v92
	ds_read_b128 v[4:7], v93 offset:32768
	ds_read_b128 v[8:11], v92 offset:4096
	ds_read_b128 v[12:15], v93 offset:36864
	ds_read_b128 v[162:165], v90
	ds_read_b128 v[166:169], v91 offset:32768
	ds_read_b128 v[170:173], v90 offset:4096
	ds_read_b128 v[174:177], v91 offset:36864
	s_waitcnt lgkmcnt(6)
	v_mfma_f32_32x32x16_bf16 v[48:63], v[0:3], v[4:7], 0
	s_waitcnt lgkmcnt(4)
	v_mfma_f32_32x32x16_bf16 v[32:47], v[0:3], v[12:15], 0
	v_mfma_f32_32x32x16_bf16 v[16:31], v[8:11], v[4:7], 0
	v_mfma_f32_32x32x16_bf16 v[0:15], v[8:11], v[12:15], 0
	s_waitcnt lgkmcnt(2)
	v_mfma_f32_32x32x16_bf16 v[48:63], v[162:165], v[166:169], v[48:63]
	s_waitcnt lgkmcnt(0)
	v_mfma_f32_32x32x16_bf16 v[32:47], v[162:165], v[174:177], v[32:47]
	v_mfma_f32_32x32x16_bf16 v[16:31], v[170:173], v[166:169], v[16:31]
	v_mfma_f32_32x32x16_bf16 v[0:15], v[170:173], v[174:177], v[0:15]
	ds_read_b128 v[162:165], v88
	ds_read_b128 v[166:169], v89 offset:32768
	ds_read_b128 v[170:173], v88 offset:4096
	ds_read_b128 v[174:177], v89 offset:36864
	s_waitcnt lgkmcnt(2)
	v_mfma_f32_32x32x16_bf16 v[48:63], v[162:165], v[166:169], v[48:63]
	s_waitcnt lgkmcnt(0)
	v_mfma_f32_32x32x16_bf16 v[32:47], v[162:165], v[174:177], v[32:47]
	v_mfma_f32_32x32x16_bf16 v[16:31], v[170:173], v[166:169], v[16:31]
	v_mfma_f32_32x32x16_bf16 v[0:15], v[170:173], v[174:177], v[0:15]
	ds_read_b128 v[162:165], v86
	ds_read_b128 v[166:169], v87 offset:32768
	ds_read_b128 v[170:173], v86 offset:4096
	ds_read_b128 v[174:177], v87 offset:36864
	s_waitcnt vmcnt(15)
	ds_write_b128 v85, v[94:97] offset:16384
	s_waitcnt vmcnt(14)
	ds_write_b128 v85, v[98:101] offset:20480
	s_waitcnt vmcnt(13)
	ds_write_b128 v85, v[102:105] offset:24576
	s_waitcnt vmcnt(12)
	ds_write_b128 v85, v[106:109] offset:28672
	s_waitcnt vmcnt(11)
	ds_write_b128 v85, v[110:113] offset:49152
	s_waitcnt vmcnt(10)
	ds_write_b128 v85, v[114:117] offset:53248
	s_waitcnt vmcnt(9)
	ds_write_b128 v85, v[118:121] offset:57344
	s_waitcnt vmcnt(8)
	ds_write_b128 v85, v[122:125] offset:61440
	s_waitcnt lgkmcnt(0)
	s_barrier
	global_load_dwordx4 v[94:97], v[70:71], off offset:384
	global_load_dwordx4 v[98:101], v[72:73], off offset:384
	global_load_dwordx4 v[102:105], v[66:67], off offset:384
	global_load_dwordx4 v[106:109], v[68:69], off offset:384
	global_load_dwordx4 v[110:113], v[74:75], off offset:384
	global_load_dwordx4 v[114:117], v[76:77], off offset:384
	global_load_dwordx4 v[118:121], v[78:79], off offset:384
	global_load_dwordx4 v[122:125], v[80:81], off offset:384
	v_mfma_f32_32x32x16_bf16 v[48:63], v[162:165], v[166:169], v[48:63]
	v_mfma_f32_32x32x16_bf16 v[32:47], v[162:165], v[174:177], v[32:47]
	v_mfma_f32_32x32x16_bf16 v[16:31], v[170:173], v[166:169], v[16:31]
	v_mfma_f32_32x32x16_bf16 v[0:15], v[170:173], v[174:177], v[0:15]
	ds_read_b128 v[162:165], v92 offset:16384
	ds_read_b128 v[166:169], v93 offset:49152
	ds_read_b128 v[170:173], v92 offset:20480
	ds_read_b128 v[174:177], v93 offset:53248
	s_waitcnt lgkmcnt(2)
	v_mfma_f32_32x32x16_bf16 v[48:63], v[162:165], v[166:169], v[48:63]
	s_waitcnt lgkmcnt(0)
	v_mfma_f32_32x32x16_bf16 v[32:47], v[162:165], v[174:177], v[32:47]
	v_mfma_f32_32x32x16_bf16 v[16:31], v[170:173], v[166:169], v[16:31]
	v_mfma_f32_32x32x16_bf16 v[0:15], v[170:173], v[174:177], v[0:15]
	ds_read_b128 v[162:165], v90 offset:16384
	ds_read_b128 v[166:169], v91 offset:49152
	ds_read_b128 v[170:173], v90 offset:20480
	ds_read_b128 v[174:177], v91 offset:53248
	s_waitcnt lgkmcnt(2)
	v_mfma_f32_32x32x16_bf16 v[48:63], v[162:165], v[166:169], v[48:63]
	s_waitcnt lgkmcnt(0)
	v_mfma_f32_32x32x16_bf16 v[32:47], v[162:165], v[174:177], v[32:47]
	v_mfma_f32_32x32x16_bf16 v[16:31], v[170:173], v[166:169], v[16:31]
	v_mfma_f32_32x32x16_bf16 v[0:15], v[170:173], v[174:177], v[0:15]
	ds_read_b128 v[162:165], v88 offset:16384
	ds_read_b128 v[166:169], v89 offset:49152
	ds_read_b128 v[170:173], v88 offset:20480
	ds_read_b128 v[174:177], v89 offset:53248
	s_waitcnt lgkmcnt(2)
	v_mfma_f32_32x32x16_bf16 v[48:63], v[162:165], v[166:169], v[48:63]
	s_waitcnt lgkmcnt(0)
	v_mfma_f32_32x32x16_bf16 v[32:47], v[162:165], v[174:177], v[32:47]
	v_mfma_f32_32x32x16_bf16 v[16:31], v[170:173], v[166:169], v[16:31]
	v_mfma_f32_32x32x16_bf16 v[0:15], v[170:173], v[174:177], v[0:15]
	ds_read_b128 v[162:165], v86 offset:16384
	ds_read_b128 v[166:169], v87 offset:49152
	ds_read_b128 v[170:173], v86 offset:20480
	ds_read_b128 v[174:177], v87 offset:53248
	s_waitcnt vmcnt(15)
	ds_write_b128 v85, v[126:129]
	s_waitcnt vmcnt(14)
	ds_write_b128 v85, v[130:133] offset:4096
	s_waitcnt vmcnt(13)
	ds_write_b128 v85, v[136:139] offset:8192
	s_waitcnt vmcnt(12)
	ds_write_b128 v85, v[140:143] offset:12288
	s_waitcnt vmcnt(11)
	ds_write_b128 v85, v[144:147] offset:32768
	s_waitcnt vmcnt(10)
	ds_write_b128 v85, v[150:153] offset:36864
	s_waitcnt vmcnt(9)
	ds_write_b128 v85, v[154:157] offset:40960
	s_waitcnt vmcnt(8)
	ds_write_b128 v85, v[158:161] offset:45056
	s_waitcnt lgkmcnt(0)
	s_barrier
	global_load_dwordx4 v[126:129], v[70:71], off offset:512
	global_load_dwordx4 v[130:133], v[72:73], off offset:512
	global_load_dwordx4 v[136:139], v[66:67], off offset:512
	global_load_dwordx4 v[140:143], v[68:69], off offset:512
	global_load_dwordx4 v[144:147], v[74:75], off offset:512
	global_load_dwordx4 v[150:153], v[76:77], off offset:512
	global_load_dwordx4 v[154:157], v[78:79], off offset:512
	global_load_dwordx4 v[158:161], v[80:81], off offset:512
	v_mfma_f32_32x32x16_bf16 v[48:63], v[162:165], v[166:169], v[48:63]
	v_mfma_f32_32x32x16_bf16 v[32:47], v[162:165], v[174:177], v[32:47]
	v_mfma_f32_32x32x16_bf16 v[16:31], v[170:173], v[166:169], v[16:31]
	v_mfma_f32_32x32x16_bf16 v[0:15], v[170:173], v[174:177], v[0:15]
	ds_read_b128 v[162:165], v92
	ds_read_b128 v[166:169], v93 offset:32768
	ds_read_b128 v[170:173], v92 offset:4096
	ds_read_b128 v[174:177], v93 offset:36864
	s_waitcnt lgkmcnt(2)
	v_mfma_f32_32x32x16_bf16 v[48:63], v[162:165], v[166:169], v[48:63]
	s_waitcnt lgkmcnt(0)
	v_mfma_f32_32x32x16_bf16 v[32:47], v[162:165], v[174:177], v[32:47]
	v_mfma_f32_32x32x16_bf16 v[16:31], v[170:173], v[166:169], v[16:31]
	v_mfma_f32_32x32x16_bf16 v[0:15], v[170:173], v[174:177], v[0:15]
	ds_read_b128 v[162:165], v90
	ds_read_b128 v[166:169], v91 offset:32768
	ds_read_b128 v[170:173], v90 offset:4096
	ds_read_b128 v[174:177], v91 offset:36864
	s_waitcnt lgkmcnt(2)
	v_mfma_f32_32x32x16_bf16 v[48:63], v[162:165], v[166:169], v[48:63]
	s_waitcnt lgkmcnt(0)
	v_mfma_f32_32x32x16_bf16 v[32:47], v[162:165], v[174:177], v[32:47]
	v_mfma_f32_32x32x16_bf16 v[16:31], v[170:173], v[166:169], v[16:31]
	v_mfma_f32_32x32x16_bf16 v[0:15], v[170:173], v[174:177], v[0:15]
	ds_read_b128 v[162:165], v88
	ds_read_b128 v[166:169], v89 offset:32768
	ds_read_b128 v[170:173], v88 offset:4096
	ds_read_b128 v[174:177], v89 offset:36864
	s_waitcnt lgkmcnt(2)
	v_mfma_f32_32x32x16_bf16 v[48:63], v[162:165], v[166:169], v[48:63]
	s_waitcnt lgkmcnt(0)
	v_mfma_f32_32x32x16_bf16 v[32:47], v[162:165], v[174:177], v[32:47]
	v_mfma_f32_32x32x16_bf16 v[16:31], v[170:173], v[166:169], v[16:31]
	v_mfma_f32_32x32x16_bf16 v[0:15], v[170:173], v[174:177], v[0:15]
	ds_read_b128 v[162:165], v86
	ds_read_b128 v[166:169], v87 offset:32768
	ds_read_b128 v[170:173], v86 offset:4096
	ds_read_b128 v[174:177], v87 offset:36864
	s_waitcnt vmcnt(13)
	ds_write_b128 v85, v[102:105] offset:16384
	ds_write_b128 v85, v[94:97] offset:20480
	ds_write_b128 v85, v[98:101] offset:24576
	s_waitcnt vmcnt(11)
	ds_write_b128 v85, v[110:113] offset:28672
	ds_write_b128 v85, v[106:109] offset:49152
	s_waitcnt vmcnt(10)
	ds_write_b128 v85, v[114:117] offset:53248
	s_waitcnt vmcnt(9)
	ds_write_b128 v85, v[118:121] offset:57344
	s_waitcnt vmcnt(8)
	ds_write_b128 v85, v[122:125] offset:61440
	s_waitcnt lgkmcnt(0)
	s_barrier
	global_load_dwordx4 v[94:97], v[70:71], off offset:640
	global_load_dwordx4 v[98:101], v[72:73], off offset:640
	global_load_dwordx4 v[102:105], v[66:67], off offset:640
	global_load_dwordx4 v[106:109], v[68:69], off offset:640
	global_load_dwordx4 v[110:113], v[74:75], off offset:640
	global_load_dwordx4 v[114:117], v[76:77], off offset:640
	global_load_dwordx4 v[118:121], v[78:79], off offset:640
	global_load_dwordx4 v[122:125], v[80:81], off offset:640
	v_mfma_f32_32x32x16_bf16 v[48:63], v[162:165], v[166:169], v[48:63]
	v_mfma_f32_32x32x16_bf16 v[32:47], v[162:165], v[174:177], v[32:47]
	v_mfma_f32_32x32x16_bf16 v[16:31], v[170:173], v[166:169], v[16:31]
	v_mfma_f32_32x32x16_bf16 v[0:15], v[170:173], v[174:177], v[0:15]
	ds_read_b128 v[162:165], v92 offset:16384
	ds_read_b128 v[166:169], v93 offset:49152
	ds_read_b128 v[170:173], v92 offset:20480
	ds_read_b128 v[174:177], v93 offset:53248
	s_waitcnt lgkmcnt(2)
	v_mfma_f32_32x32x16_bf16 v[48:63], v[162:165], v[166:169], v[48:63]
	s_waitcnt lgkmcnt(0)
	v_mfma_f32_32x32x16_bf16 v[32:47], v[162:165], v[174:177], v[32:47]
	v_mfma_f32_32x32x16_bf16 v[16:31], v[170:173], v[166:169], v[16:31]
	v_mfma_f32_32x32x16_bf16 v[0:15], v[170:173], v[174:177], v[0:15]
	ds_read_b128 v[162:165], v90 offset:16384
	ds_read_b128 v[166:169], v91 offset:49152
	ds_read_b128 v[170:173], v90 offset:20480
	ds_read_b128 v[174:177], v91 offset:53248
	s_waitcnt lgkmcnt(2)
	v_mfma_f32_32x32x16_bf16 v[48:63], v[162:165], v[166:169], v[48:63]
	s_waitcnt lgkmcnt(0)
	v_mfma_f32_32x32x16_bf16 v[32:47], v[162:165], v[174:177], v[32:47]
	v_mfma_f32_32x32x16_bf16 v[16:31], v[170:173], v[166:169], v[16:31]
	v_mfma_f32_32x32x16_bf16 v[0:15], v[170:173], v[174:177], v[0:15]
	ds_read_b128 v[162:165], v88 offset:16384
	ds_read_b128 v[166:169], v89 offset:49152
	ds_read_b128 v[170:173], v88 offset:20480
	ds_read_b128 v[174:177], v89 offset:53248
	s_waitcnt lgkmcnt(2)
	v_mfma_f32_32x32x16_bf16 v[48:63], v[162:165], v[166:169], v[48:63]
	s_waitcnt lgkmcnt(0)
	v_mfma_f32_32x32x16_bf16 v[32:47], v[162:165], v[174:177], v[32:47]
	v_mfma_f32_32x32x16_bf16 v[16:31], v[170:173], v[166:169], v[16:31]
	v_mfma_f32_32x32x16_bf16 v[0:15], v[170:173], v[174:177], v[0:15]
	ds_read_b128 v[162:165], v86 offset:16384
	ds_read_b128 v[166:169], v87 offset:49152
	ds_read_b128 v[170:173], v86 offset:20480
	ds_read_b128 v[174:177], v87 offset:53248
	s_waitcnt vmcnt(13)
	ds_write_b128 v85, v[136:139]
	ds_write_b128 v85, v[126:129] offset:4096
	ds_write_b128 v85, v[130:133] offset:8192
	s_waitcnt vmcnt(11)
	ds_write_b128 v85, v[144:147] offset:12288
	ds_write_b128 v85, v[140:143] offset:32768
	s_waitcnt vmcnt(10)
	ds_write_b128 v85, v[150:153] offset:36864
	s_waitcnt vmcnt(9)
	ds_write_b128 v85, v[154:157] offset:40960
	s_waitcnt vmcnt(8)
	ds_write_b128 v85, v[158:161] offset:45056
	s_waitcnt lgkmcnt(0)
	s_barrier
	global_load_dwordx4 v[126:129], v[70:71], off offset:768
	global_load_dwordx4 v[130:133], v[72:73], off offset:768
	global_load_dwordx4 v[136:139], v[66:67], off offset:768
	global_load_dwordx4 v[140:143], v[68:69], off offset:768
	global_load_dwordx4 v[144:147], v[74:75], off offset:768
	global_load_dwordx4 v[150:153], v[76:77], off offset:768
	global_load_dwordx4 v[154:157], v[78:79], off offset:768
	global_load_dwordx4 v[158:161], v[80:81], off offset:768
	v_mfma_f32_32x32x16_bf16 v[48:63], v[162:165], v[166:169], v[48:63]
	v_mfma_f32_32x32x16_bf16 v[32:47], v[162:165], v[174:177], v[32:47]
	v_mfma_f32_32x32x16_bf16 v[16:31], v[170:173], v[166:169], v[16:31]
	v_mfma_f32_32x32x16_bf16 v[0:15], v[170:173], v[174:177], v[0:15]
	ds_read_b128 v[162:165], v92
	ds_read_b128 v[166:169], v93 offset:32768
	ds_read_b128 v[170:173], v92 offset:4096
	ds_read_b128 v[174:177], v93 offset:36864
	s_waitcnt lgkmcnt(2)
	v_mfma_f32_32x32x16_bf16 v[48:63], v[162:165], v[166:169], v[48:63]
	s_waitcnt lgkmcnt(0)
	v_mfma_f32_32x32x16_bf16 v[32:47], v[162:165], v[174:177], v[32:47]
	v_mfma_f32_32x32x16_bf16 v[16:31], v[170:173], v[166:169], v[16:31]
	v_mfma_f32_32x32x16_bf16 v[0:15], v[170:173], v[174:177], v[0:15]
	ds_read_b128 v[162:165], v90
	ds_read_b128 v[166:169], v91 offset:32768
	ds_read_b128 v[170:173], v90 offset:4096
	ds_read_b128 v[174:177], v91 offset:36864
	s_waitcnt lgkmcnt(2)
	v_mfma_f32_32x32x16_bf16 v[48:63], v[162:165], v[166:169], v[48:63]
	s_waitcnt lgkmcnt(0)
	v_mfma_f32_32x32x16_bf16 v[32:47], v[162:165], v[174:177], v[32:47]
	v_mfma_f32_32x32x16_bf16 v[16:31], v[170:173], v[166:169], v[16:31]
	v_mfma_f32_32x32x16_bf16 v[0:15], v[170:173], v[174:177], v[0:15]
	ds_read_b128 v[162:165], v88
	ds_read_b128 v[166:169], v89 offset:32768
	ds_read_b128 v[170:173], v88 offset:4096
	ds_read_b128 v[174:177], v89 offset:36864
	s_waitcnt lgkmcnt(2)
	v_mfma_f32_32x32x16_bf16 v[48:63], v[162:165], v[166:169], v[48:63]
	s_waitcnt lgkmcnt(0)
	v_mfma_f32_32x32x16_bf16 v[32:47], v[162:165], v[174:177], v[32:47]
	v_mfma_f32_32x32x16_bf16 v[16:31], v[170:173], v[166:169], v[16:31]
	v_mfma_f32_32x32x16_bf16 v[0:15], v[170:173], v[174:177], v[0:15]
	ds_read_b128 v[162:165], v86
	ds_read_b128 v[166:169], v87 offset:32768
	ds_read_b128 v[170:173], v86 offset:4096
	ds_read_b128 v[174:177], v87 offset:36864
	s_waitcnt vmcnt(13)
	ds_write_b128 v85, v[102:105] offset:16384
	ds_write_b128 v85, v[94:97] offset:20480
	ds_write_b128 v85, v[98:101] offset:24576
	s_waitcnt vmcnt(11)
	ds_write_b128 v85, v[110:113] offset:28672
	ds_write_b128 v85, v[106:109] offset:49152
	s_waitcnt vmcnt(10)
	ds_write_b128 v85, v[114:117] offset:53248
	s_waitcnt vmcnt(9)
	ds_write_b128 v85, v[118:121] offset:57344
	s_waitcnt vmcnt(8)
	ds_write_b128 v85, v[122:125] offset:61440
	s_waitcnt lgkmcnt(0)
	s_barrier
	global_load_dwordx4 v[94:97], v[70:71], off offset:896
	global_load_dwordx4 v[98:101], v[72:73], off offset:896
	global_load_dwordx4 v[102:105], v[66:67], off offset:896
	global_load_dwordx4 v[106:109], v[68:69], off offset:896
	global_load_dwordx4 v[110:113], v[74:75], off offset:896
	global_load_dwordx4 v[114:117], v[76:77], off offset:896
	global_load_dwordx4 v[118:121], v[78:79], off offset:896
	global_load_dwordx4 v[122:125], v[80:81], off offset:896
	v_mfma_f32_32x32x16_bf16 v[48:63], v[162:165], v[166:169], v[48:63]
	v_mfma_f32_32x32x16_bf16 v[32:47], v[162:165], v[174:177], v[32:47]
	v_mfma_f32_32x32x16_bf16 v[16:31], v[170:173], v[166:169], v[16:31]
	v_mfma_f32_32x32x16_bf16 v[0:15], v[170:173], v[174:177], v[0:15]
	ds_read_b128 v[162:165], v92 offset:16384
	ds_read_b128 v[166:169], v93 offset:49152
	ds_read_b128 v[170:173], v92 offset:20480
	ds_read_b128 v[174:177], v93 offset:53248
	s_waitcnt lgkmcnt(2)
	v_mfma_f32_32x32x16_bf16 v[48:63], v[162:165], v[166:169], v[48:63]
	s_waitcnt lgkmcnt(0)
	v_mfma_f32_32x32x16_bf16 v[32:47], v[162:165], v[174:177], v[32:47]
	v_mfma_f32_32x32x16_bf16 v[16:31], v[170:173], v[166:169], v[16:31]
	v_mfma_f32_32x32x16_bf16 v[0:15], v[170:173], v[174:177], v[0:15]
	ds_read_b128 v[162:165], v90 offset:16384
	ds_read_b128 v[166:169], v91 offset:49152
	ds_read_b128 v[170:173], v90 offset:20480
	ds_read_b128 v[174:177], v91 offset:53248
	s_waitcnt lgkmcnt(2)
	v_mfma_f32_32x32x16_bf16 v[48:63], v[162:165], v[166:169], v[48:63]
	s_waitcnt lgkmcnt(0)
	v_mfma_f32_32x32x16_bf16 v[32:47], v[162:165], v[174:177], v[32:47]
	v_mfma_f32_32x32x16_bf16 v[16:31], v[170:173], v[166:169], v[16:31]
	v_mfma_f32_32x32x16_bf16 v[0:15], v[170:173], v[174:177], v[0:15]
	ds_read_b128 v[162:165], v88 offset:16384
	ds_read_b128 v[166:169], v89 offset:49152
	ds_read_b128 v[170:173], v88 offset:20480
	ds_read_b128 v[174:177], v89 offset:53248
	s_waitcnt lgkmcnt(2)
	v_mfma_f32_32x32x16_bf16 v[48:63], v[162:165], v[166:169], v[48:63]
	s_waitcnt lgkmcnt(0)
	v_mfma_f32_32x32x16_bf16 v[32:47], v[162:165], v[174:177], v[32:47]
	v_mfma_f32_32x32x16_bf16 v[16:31], v[170:173], v[166:169], v[16:31]
	v_mfma_f32_32x32x16_bf16 v[0:15], v[170:173], v[174:177], v[0:15]
	ds_read_b128 v[162:165], v86 offset:16384
	ds_read_b128 v[166:169], v87 offset:49152
	ds_read_b128 v[170:173], v86 offset:20480
	ds_read_b128 v[174:177], v87 offset:53248
	s_waitcnt vmcnt(13)
	ds_write_b128 v85, v[136:139]
	ds_write_b128 v85, v[126:129] offset:4096
	ds_write_b128 v85, v[130:133] offset:8192
	s_waitcnt vmcnt(11)
	ds_write_b128 v85, v[144:147] offset:12288
	ds_write_b128 v85, v[140:143] offset:32768
	s_waitcnt vmcnt(10)
	ds_write_b128 v85, v[150:153] offset:36864
	s_waitcnt vmcnt(9)
	ds_write_b128 v85, v[154:157] offset:40960
	s_waitcnt vmcnt(8)
	ds_write_b128 v85, v[158:161] offset:45056
	s_waitcnt lgkmcnt(0)
	s_barrier
	global_load_dwordx4 v[126:129], v[70:71], off offset:1024
	global_load_dwordx4 v[130:133], v[72:73], off offset:1024
	global_load_dwordx4 v[136:139], v[66:67], off offset:1024
	global_load_dwordx4 v[140:143], v[68:69], off offset:1024
	global_load_dwordx4 v[144:147], v[74:75], off offset:1024
	global_load_dwordx4 v[150:153], v[76:77], off offset:1024
	global_load_dwordx4 v[154:157], v[78:79], off offset:1024
	global_load_dwordx4 v[158:161], v[80:81], off offset:1024
	v_mfma_f32_32x32x16_bf16 v[48:63], v[162:165], v[166:169], v[48:63]
	v_mfma_f32_32x32x16_bf16 v[32:47], v[162:165], v[174:177], v[32:47]
	v_mfma_f32_32x32x16_bf16 v[16:31], v[170:173], v[166:169], v[16:31]
	v_mfma_f32_32x32x16_bf16 v[0:15], v[170:173], v[174:177], v[0:15]
	ds_read_b128 v[162:165], v92
	ds_read_b128 v[166:169], v93 offset:32768
	ds_read_b128 v[170:173], v92 offset:4096
	ds_read_b128 v[174:177], v93 offset:36864
	s_waitcnt lgkmcnt(2)
	v_mfma_f32_32x32x16_bf16 v[48:63], v[162:165], v[166:169], v[48:63]
	s_waitcnt lgkmcnt(0)
	v_mfma_f32_32x32x16_bf16 v[32:47], v[162:165], v[174:177], v[32:47]
	v_mfma_f32_32x32x16_bf16 v[16:31], v[170:173], v[166:169], v[16:31]
	v_mfma_f32_32x32x16_bf16 v[0:15], v[170:173], v[174:177], v[0:15]
	ds_read_b128 v[162:165], v90
	ds_read_b128 v[166:169], v91 offset:32768
	ds_read_b128 v[170:173], v90 offset:4096
	ds_read_b128 v[174:177], v91 offset:36864
	s_waitcnt lgkmcnt(2)
	v_mfma_f32_32x32x16_bf16 v[48:63], v[162:165], v[166:169], v[48:63]
	s_waitcnt lgkmcnt(0)
	v_mfma_f32_32x32x16_bf16 v[32:47], v[162:165], v[174:177], v[32:47]
	v_mfma_f32_32x32x16_bf16 v[16:31], v[170:173], v[166:169], v[16:31]
	v_mfma_f32_32x32x16_bf16 v[0:15], v[170:173], v[174:177], v[0:15]
	ds_read_b128 v[162:165], v88
	ds_read_b128 v[166:169], v89 offset:32768
	ds_read_b128 v[170:173], v88 offset:4096
	ds_read_b128 v[174:177], v89 offset:36864
	s_waitcnt lgkmcnt(2)
	v_mfma_f32_32x32x16_bf16 v[48:63], v[162:165], v[166:169], v[48:63]
	s_waitcnt lgkmcnt(0)
	v_mfma_f32_32x32x16_bf16 v[32:47], v[162:165], v[174:177], v[32:47]
	v_mfma_f32_32x32x16_bf16 v[16:31], v[170:173], v[166:169], v[16:31]
	v_mfma_f32_32x32x16_bf16 v[0:15], v[170:173], v[174:177], v[0:15]
	ds_read_b128 v[162:165], v86
	ds_read_b128 v[166:169], v87 offset:32768
	ds_read_b128 v[170:173], v86 offset:4096
	ds_read_b128 v[174:177], v87 offset:36864
	s_waitcnt vmcnt(13)
	ds_write_b128 v85, v[102:105] offset:16384
	ds_write_b128 v85, v[94:97] offset:20480
	ds_write_b128 v85, v[98:101] offset:24576
	s_waitcnt vmcnt(11)
	ds_write_b128 v85, v[110:113] offset:28672
	ds_write_b128 v85, v[106:109] offset:49152
	s_waitcnt vmcnt(10)
	ds_write_b128 v85, v[114:117] offset:53248
	s_waitcnt vmcnt(9)
	ds_write_b128 v85, v[118:121] offset:57344
	s_waitcnt vmcnt(8)
	ds_write_b128 v85, v[122:125] offset:61440
	s_waitcnt lgkmcnt(0)
	s_barrier
	global_load_dwordx4 v[94:97], v[70:71], off offset:1152
	global_load_dwordx4 v[98:101], v[72:73], off offset:1152
	global_load_dwordx4 v[102:105], v[66:67], off offset:1152
	global_load_dwordx4 v[106:109], v[68:69], off offset:1152
	global_load_dwordx4 v[110:113], v[74:75], off offset:1152
	global_load_dwordx4 v[114:117], v[76:77], off offset:1152
	global_load_dwordx4 v[118:121], v[78:79], off offset:1152
	global_load_dwordx4 v[122:125], v[80:81], off offset:1152
	v_mfma_f32_32x32x16_bf16 v[48:63], v[162:165], v[166:169], v[48:63]
	v_mfma_f32_32x32x16_bf16 v[32:47], v[162:165], v[174:177], v[32:47]
	v_mfma_f32_32x32x16_bf16 v[16:31], v[170:173], v[166:169], v[16:31]
	v_mfma_f32_32x32x16_bf16 v[0:15], v[170:173], v[174:177], v[0:15]
	ds_read_b128 v[162:165], v92 offset:16384
	ds_read_b128 v[166:169], v93 offset:49152
	ds_read_b128 v[170:173], v92 offset:20480
	ds_read_b128 v[174:177], v93 offset:53248
	s_waitcnt lgkmcnt(2)
	v_mfma_f32_32x32x16_bf16 v[48:63], v[162:165], v[166:169], v[48:63]
	s_waitcnt lgkmcnt(0)
	v_mfma_f32_32x32x16_bf16 v[32:47], v[162:165], v[174:177], v[32:47]
	v_mfma_f32_32x32x16_bf16 v[16:31], v[170:173], v[166:169], v[16:31]
	v_mfma_f32_32x32x16_bf16 v[0:15], v[170:173], v[174:177], v[0:15]
	ds_read_b128 v[162:165], v90 offset:16384
	ds_read_b128 v[166:169], v91 offset:49152
	ds_read_b128 v[170:173], v90 offset:20480
	ds_read_b128 v[174:177], v91 offset:53248
	s_waitcnt lgkmcnt(2)
	v_mfma_f32_32x32x16_bf16 v[48:63], v[162:165], v[166:169], v[48:63]
	s_waitcnt lgkmcnt(0)
	v_mfma_f32_32x32x16_bf16 v[32:47], v[162:165], v[174:177], v[32:47]
	v_mfma_f32_32x32x16_bf16 v[16:31], v[170:173], v[166:169], v[16:31]
	v_mfma_f32_32x32x16_bf16 v[0:15], v[170:173], v[174:177], v[0:15]
	ds_read_b128 v[162:165], v88 offset:16384
	ds_read_b128 v[166:169], v89 offset:49152
	ds_read_b128 v[170:173], v88 offset:20480
	ds_read_b128 v[174:177], v89 offset:53248
	s_waitcnt lgkmcnt(2)
	v_mfma_f32_32x32x16_bf16 v[48:63], v[162:165], v[166:169], v[48:63]
	s_waitcnt lgkmcnt(0)
	v_mfma_f32_32x32x16_bf16 v[32:47], v[162:165], v[174:177], v[32:47]
	v_mfma_f32_32x32x16_bf16 v[16:31], v[170:173], v[166:169], v[16:31]
	v_mfma_f32_32x32x16_bf16 v[0:15], v[170:173], v[174:177], v[0:15]
	ds_read_b128 v[162:165], v86 offset:16384
	ds_read_b128 v[166:169], v87 offset:49152
	ds_read_b128 v[170:173], v86 offset:20480
	ds_read_b128 v[174:177], v87 offset:53248
	s_waitcnt vmcnt(13)
	ds_write_b128 v85, v[136:139]
	ds_write_b128 v85, v[126:129] offset:4096
	ds_write_b128 v85, v[130:133] offset:8192
	s_waitcnt vmcnt(11)
	ds_write_b128 v85, v[144:147] offset:12288
	ds_write_b128 v85, v[140:143] offset:32768
	s_waitcnt vmcnt(10)
	ds_write_b128 v85, v[150:153] offset:36864
	s_waitcnt vmcnt(9)
	ds_write_b128 v85, v[154:157] offset:40960
	s_waitcnt vmcnt(8)
	ds_write_b128 v85, v[158:161] offset:45056
	s_waitcnt lgkmcnt(0)
	s_barrier
	global_load_dwordx4 v[126:129], v[70:71], off offset:1280
	global_load_dwordx4 v[130:133], v[72:73], off offset:1280
	global_load_dwordx4 v[136:139], v[66:67], off offset:1280
	global_load_dwordx4 v[140:143], v[68:69], off offset:1280
	global_load_dwordx4 v[144:147], v[74:75], off offset:1280
	global_load_dwordx4 v[150:153], v[76:77], off offset:1280
	global_load_dwordx4 v[154:157], v[78:79], off offset:1280
	global_load_dwordx4 v[158:161], v[80:81], off offset:1280
	v_mfma_f32_32x32x16_bf16 v[48:63], v[162:165], v[166:169], v[48:63]
	v_mfma_f32_32x32x16_bf16 v[32:47], v[162:165], v[174:177], v[32:47]
	v_mfma_f32_32x32x16_bf16 v[16:31], v[170:173], v[166:169], v[16:31]
	v_mfma_f32_32x32x16_bf16 v[0:15], v[170:173], v[174:177], v[0:15]
	ds_read_b128 v[162:165], v92
	ds_read_b128 v[166:169], v93 offset:32768
	ds_read_b128 v[170:173], v92 offset:4096
	ds_read_b128 v[174:177], v93 offset:36864
	s_waitcnt lgkmcnt(2)
	v_mfma_f32_32x32x16_bf16 v[48:63], v[162:165], v[166:169], v[48:63]
	s_waitcnt lgkmcnt(0)
	v_mfma_f32_32x32x16_bf16 v[32:47], v[162:165], v[174:177], v[32:47]
	v_mfma_f32_32x32x16_bf16 v[16:31], v[170:173], v[166:169], v[16:31]
	v_mfma_f32_32x32x16_bf16 v[0:15], v[170:173], v[174:177], v[0:15]
	ds_read_b128 v[162:165], v90
	ds_read_b128 v[166:169], v91 offset:32768
	ds_read_b128 v[170:173], v90 offset:4096
	ds_read_b128 v[174:177], v91 offset:36864
	s_waitcnt lgkmcnt(2)
	v_mfma_f32_32x32x16_bf16 v[48:63], v[162:165], v[166:169], v[48:63]
	s_waitcnt lgkmcnt(0)
	v_mfma_f32_32x32x16_bf16 v[32:47], v[162:165], v[174:177], v[32:47]
	v_mfma_f32_32x32x16_bf16 v[16:31], v[170:173], v[166:169], v[16:31]
	v_mfma_f32_32x32x16_bf16 v[0:15], v[170:173], v[174:177], v[0:15]
	ds_read_b128 v[162:165], v88
	ds_read_b128 v[166:169], v89 offset:32768
	ds_read_b128 v[170:173], v88 offset:4096
	ds_read_b128 v[174:177], v89 offset:36864
	s_waitcnt lgkmcnt(2)
	v_mfma_f32_32x32x16_bf16 v[48:63], v[162:165], v[166:169], v[48:63]
	s_waitcnt lgkmcnt(0)
	v_mfma_f32_32x32x16_bf16 v[32:47], v[162:165], v[174:177], v[32:47]
	v_mfma_f32_32x32x16_bf16 v[16:31], v[170:173], v[166:169], v[16:31]
	v_mfma_f32_32x32x16_bf16 v[0:15], v[170:173], v[174:177], v[0:15]
	ds_read_b128 v[162:165], v86
	ds_read_b128 v[166:169], v87 offset:32768
	ds_read_b128 v[170:173], v86 offset:4096
	ds_read_b128 v[174:177], v87 offset:36864
	s_waitcnt vmcnt(13)
	ds_write_b128 v85, v[102:105] offset:16384
	ds_write_b128 v85, v[94:97] offset:20480
	ds_write_b128 v85, v[98:101] offset:24576
	s_waitcnt vmcnt(11)
	ds_write_b128 v85, v[110:113] offset:28672
	ds_write_b128 v85, v[106:109] offset:49152
	s_waitcnt vmcnt(10)
	ds_write_b128 v85, v[114:117] offset:53248
	s_waitcnt vmcnt(9)
	ds_write_b128 v85, v[118:121] offset:57344
	s_waitcnt vmcnt(8)
	ds_write_b128 v85, v[122:125] offset:61440
	s_waitcnt lgkmcnt(0)
	s_barrier
	global_load_dwordx4 v[94:97], v[70:71], off offset:1408
	global_load_dwordx4 v[98:101], v[72:73], off offset:1408
	global_load_dwordx4 v[102:105], v[66:67], off offset:1408
	global_load_dwordx4 v[106:109], v[68:69], off offset:1408
	global_load_dwordx4 v[110:113], v[74:75], off offset:1408
	global_load_dwordx4 v[114:117], v[76:77], off offset:1408
	global_load_dwordx4 v[118:121], v[78:79], off offset:1408
	global_load_dwordx4 v[122:125], v[80:81], off offset:1408
	v_mfma_f32_32x32x16_bf16 v[48:63], v[162:165], v[166:169], v[48:63]
	v_mfma_f32_32x32x16_bf16 v[32:47], v[162:165], v[174:177], v[32:47]
	v_mfma_f32_32x32x16_bf16 v[16:31], v[170:173], v[166:169], v[16:31]
	v_mfma_f32_32x32x16_bf16 v[0:15], v[170:173], v[174:177], v[0:15]
	ds_read_b128 v[162:165], v92 offset:16384
	ds_read_b128 v[166:169], v93 offset:49152
	ds_read_b128 v[170:173], v92 offset:20480
	ds_read_b128 v[174:177], v93 offset:53248
	s_waitcnt lgkmcnt(2)
	v_mfma_f32_32x32x16_bf16 v[48:63], v[162:165], v[166:169], v[48:63]
	s_waitcnt lgkmcnt(0)
	v_mfma_f32_32x32x16_bf16 v[32:47], v[162:165], v[174:177], v[32:47]
	v_mfma_f32_32x32x16_bf16 v[16:31], v[170:173], v[166:169], v[16:31]
	v_mfma_f32_32x32x16_bf16 v[0:15], v[170:173], v[174:177], v[0:15]
	ds_read_b128 v[162:165], v90 offset:16384
	ds_read_b128 v[166:169], v91 offset:49152
	ds_read_b128 v[170:173], v90 offset:20480
	ds_read_b128 v[174:177], v91 offset:53248
	s_waitcnt lgkmcnt(2)
	v_mfma_f32_32x32x16_bf16 v[48:63], v[162:165], v[166:169], v[48:63]
	s_waitcnt lgkmcnt(0)
	v_mfma_f32_32x32x16_bf16 v[32:47], v[162:165], v[174:177], v[32:47]
	v_mfma_f32_32x32x16_bf16 v[16:31], v[170:173], v[166:169], v[16:31]
	v_mfma_f32_32x32x16_bf16 v[0:15], v[170:173], v[174:177], v[0:15]
	ds_read_b128 v[162:165], v88 offset:16384
	ds_read_b128 v[166:169], v89 offset:49152
	ds_read_b128 v[170:173], v88 offset:20480
	ds_read_b128 v[174:177], v89 offset:53248
	s_waitcnt lgkmcnt(2)
	v_mfma_f32_32x32x16_bf16 v[48:63], v[162:165], v[166:169], v[48:63]
	s_waitcnt lgkmcnt(0)
	v_mfma_f32_32x32x16_bf16 v[32:47], v[162:165], v[174:177], v[32:47]
	v_mfma_f32_32x32x16_bf16 v[16:31], v[170:173], v[166:169], v[16:31]
	v_mfma_f32_32x32x16_bf16 v[0:15], v[170:173], v[174:177], v[0:15]
	ds_read_b128 v[162:165], v86 offset:16384
	ds_read_b128 v[166:169], v87 offset:49152
	ds_read_b128 v[170:173], v86 offset:20480
	ds_read_b128 v[174:177], v87 offset:53248
	s_waitcnt vmcnt(13)
	ds_write_b128 v85, v[136:139]
	ds_write_b128 v85, v[126:129] offset:4096
	ds_write_b128 v85, v[130:133] offset:8192
	s_waitcnt vmcnt(11)
	ds_write_b128 v85, v[144:147] offset:12288
	ds_write_b128 v85, v[140:143] offset:32768
	s_waitcnt vmcnt(10)
	ds_write_b128 v85, v[150:153] offset:36864
	s_waitcnt vmcnt(9)
	ds_write_b128 v85, v[154:157] offset:40960
	s_waitcnt vmcnt(8)
	ds_write_b128 v85, v[158:161] offset:45056
	s_waitcnt lgkmcnt(0)
	s_barrier
	global_load_dwordx4 v[126:129], v[70:71], off offset:1536
	global_load_dwordx4 v[130:133], v[72:73], off offset:1536
	global_load_dwordx4 v[136:139], v[66:67], off offset:1536
	global_load_dwordx4 v[140:143], v[68:69], off offset:1536
	global_load_dwordx4 v[144:147], v[74:75], off offset:1536
	global_load_dwordx4 v[150:153], v[76:77], off offset:1536
	global_load_dwordx4 v[154:157], v[78:79], off offset:1536
	global_load_dwordx4 v[158:161], v[80:81], off offset:1536
	v_mfma_f32_32x32x16_bf16 v[48:63], v[162:165], v[166:169], v[48:63]
	v_mfma_f32_32x32x16_bf16 v[32:47], v[162:165], v[174:177], v[32:47]
	v_mfma_f32_32x32x16_bf16 v[16:31], v[170:173], v[166:169], v[16:31]
	v_mfma_f32_32x32x16_bf16 v[0:15], v[170:173], v[174:177], v[0:15]
	ds_read_b128 v[162:165], v92
	ds_read_b128 v[166:169], v93 offset:32768
	ds_read_b128 v[170:173], v92 offset:4096
	ds_read_b128 v[174:177], v93 offset:36864
	s_waitcnt lgkmcnt(2)
	v_mfma_f32_32x32x16_bf16 v[48:63], v[162:165], v[166:169], v[48:63]
	s_waitcnt lgkmcnt(0)
	v_mfma_f32_32x32x16_bf16 v[32:47], v[162:165], v[174:177], v[32:47]
	v_mfma_f32_32x32x16_bf16 v[16:31], v[170:173], v[166:169], v[16:31]
	v_mfma_f32_32x32x16_bf16 v[0:15], v[170:173], v[174:177], v[0:15]
	ds_read_b128 v[162:165], v90
	ds_read_b128 v[166:169], v91 offset:32768
	ds_read_b128 v[170:173], v90 offset:4096
	ds_read_b128 v[174:177], v91 offset:36864
	s_waitcnt lgkmcnt(2)
	v_mfma_f32_32x32x16_bf16 v[48:63], v[162:165], v[166:169], v[48:63]
	s_waitcnt lgkmcnt(0)
	v_mfma_f32_32x32x16_bf16 v[32:47], v[162:165], v[174:177], v[32:47]
	v_mfma_f32_32x32x16_bf16 v[16:31], v[170:173], v[166:169], v[16:31]
	v_mfma_f32_32x32x16_bf16 v[0:15], v[170:173], v[174:177], v[0:15]
	ds_read_b128 v[162:165], v88
	ds_read_b128 v[166:169], v89 offset:32768
	ds_read_b128 v[170:173], v88 offset:4096
	ds_read_b128 v[174:177], v89 offset:36864
	s_waitcnt lgkmcnt(2)
	v_mfma_f32_32x32x16_bf16 v[48:63], v[162:165], v[166:169], v[48:63]
	s_waitcnt lgkmcnt(0)
	v_mfma_f32_32x32x16_bf16 v[32:47], v[162:165], v[174:177], v[32:47]
	v_mfma_f32_32x32x16_bf16 v[16:31], v[170:173], v[166:169], v[16:31]
	v_mfma_f32_32x32x16_bf16 v[0:15], v[170:173], v[174:177], v[0:15]
	ds_read_b128 v[162:165], v86
	ds_read_b128 v[166:169], v87 offset:32768
	ds_read_b128 v[170:173], v86 offset:4096
	ds_read_b128 v[174:177], v87 offset:36864
	s_waitcnt vmcnt(13)
	ds_write_b128 v85, v[102:105] offset:16384
	ds_write_b128 v85, v[94:97] offset:20480
	ds_write_b128 v85, v[98:101] offset:24576
	s_waitcnt vmcnt(11)
	ds_write_b128 v85, v[110:113] offset:28672
	ds_write_b128 v85, v[106:109] offset:49152
	s_waitcnt vmcnt(10)
	ds_write_b128 v85, v[114:117] offset:53248
	s_waitcnt vmcnt(9)
	ds_write_b128 v85, v[118:121] offset:57344
	s_waitcnt vmcnt(8)
	ds_write_b128 v85, v[122:125] offset:61440
	s_waitcnt lgkmcnt(0)
	s_barrier
	global_load_dwordx4 v[94:97], v[70:71], off offset:1664
	global_load_dwordx4 v[98:101], v[72:73], off offset:1664
	global_load_dwordx4 v[102:105], v[66:67], off offset:1664
	global_load_dwordx4 v[106:109], v[68:69], off offset:1664
	global_load_dwordx4 v[110:113], v[74:75], off offset:1664
	global_load_dwordx4 v[114:117], v[76:77], off offset:1664
	global_load_dwordx4 v[118:121], v[78:79], off offset:1664
	global_load_dwordx4 v[122:125], v[80:81], off offset:1664
	v_mfma_f32_32x32x16_bf16 v[48:63], v[162:165], v[166:169], v[48:63]
	v_mfma_f32_32x32x16_bf16 v[32:47], v[162:165], v[174:177], v[32:47]
	v_mfma_f32_32x32x16_bf16 v[16:31], v[170:173], v[166:169], v[16:31]
	v_mfma_f32_32x32x16_bf16 v[0:15], v[170:173], v[174:177], v[0:15]
	ds_read_b128 v[162:165], v92 offset:16384
	ds_read_b128 v[166:169], v93 offset:49152
	ds_read_b128 v[170:173], v92 offset:20480
	ds_read_b128 v[174:177], v93 offset:53248
	s_waitcnt lgkmcnt(2)
	v_mfma_f32_32x32x16_bf16 v[48:63], v[162:165], v[166:169], v[48:63]
	s_waitcnt lgkmcnt(0)
	v_mfma_f32_32x32x16_bf16 v[32:47], v[162:165], v[174:177], v[32:47]
	v_mfma_f32_32x32x16_bf16 v[16:31], v[170:173], v[166:169], v[16:31]
	v_mfma_f32_32x32x16_bf16 v[0:15], v[170:173], v[174:177], v[0:15]
	ds_read_b128 v[162:165], v90 offset:16384
	ds_read_b128 v[166:169], v91 offset:49152
	ds_read_b128 v[170:173], v90 offset:20480
	ds_read_b128 v[174:177], v91 offset:53248
	s_waitcnt lgkmcnt(2)
	v_mfma_f32_32x32x16_bf16 v[48:63], v[162:165], v[166:169], v[48:63]
	s_waitcnt lgkmcnt(0)
	v_mfma_f32_32x32x16_bf16 v[32:47], v[162:165], v[174:177], v[32:47]
	v_mfma_f32_32x32x16_bf16 v[16:31], v[170:173], v[166:169], v[16:31]
	v_mfma_f32_32x32x16_bf16 v[0:15], v[170:173], v[174:177], v[0:15]
	ds_read_b128 v[162:165], v88 offset:16384
	ds_read_b128 v[166:169], v89 offset:49152
	ds_read_b128 v[170:173], v88 offset:20480
	ds_read_b128 v[174:177], v89 offset:53248
	s_waitcnt lgkmcnt(2)
	v_mfma_f32_32x32x16_bf16 v[48:63], v[162:165], v[166:169], v[48:63]
	s_waitcnt lgkmcnt(0)
	v_mfma_f32_32x32x16_bf16 v[32:47], v[162:165], v[174:177], v[32:47]
	v_mfma_f32_32x32x16_bf16 v[16:31], v[170:173], v[166:169], v[16:31]
	v_mfma_f32_32x32x16_bf16 v[0:15], v[170:173], v[174:177], v[0:15]
	ds_read_b128 v[162:165], v86 offset:16384
	ds_read_b128 v[166:169], v87 offset:49152
	ds_read_b128 v[170:173], v86 offset:20480
	ds_read_b128 v[174:177], v87 offset:53248
	s_waitcnt vmcnt(13)
	ds_write_b128 v85, v[136:139]
	ds_write_b128 v85, v[126:129] offset:4096
	ds_write_b128 v85, v[130:133] offset:8192
	s_waitcnt vmcnt(11)
	ds_write_b128 v85, v[144:147] offset:12288
	ds_write_b128 v85, v[140:143] offset:32768
	s_waitcnt vmcnt(10)
	ds_write_b128 v85, v[150:153] offset:36864
	s_waitcnt vmcnt(9)
	ds_write_b128 v85, v[154:157] offset:40960
	s_waitcnt vmcnt(8)
	ds_write_b128 v85, v[158:161] offset:45056
	s_waitcnt lgkmcnt(0)
	s_barrier
	global_load_dwordx4 v[126:129], v[70:71], off offset:1792
	global_load_dwordx4 v[130:133], v[72:73], off offset:1792
	global_load_dwordx4 v[136:139], v[66:67], off offset:1792
	global_load_dwordx4 v[140:143], v[68:69], off offset:1792
	global_load_dwordx4 v[144:147], v[74:75], off offset:1792
	global_load_dwordx4 v[150:153], v[76:77], off offset:1792
	global_load_dwordx4 v[154:157], v[78:79], off offset:1792
	global_load_dwordx4 v[158:161], v[80:81], off offset:1792
	v_mfma_f32_32x32x16_bf16 v[48:63], v[162:165], v[166:169], v[48:63]
	v_mfma_f32_32x32x16_bf16 v[32:47], v[162:165], v[174:177], v[32:47]
	v_mfma_f32_32x32x16_bf16 v[16:31], v[170:173], v[166:169], v[16:31]
	v_mfma_f32_32x32x16_bf16 v[0:15], v[170:173], v[174:177], v[0:15]
	ds_read_b128 v[162:165], v92
	ds_read_b128 v[166:169], v93 offset:32768
	ds_read_b128 v[170:173], v92 offset:4096
	ds_read_b128 v[174:177], v93 offset:36864
	s_waitcnt lgkmcnt(2)
	v_mfma_f32_32x32x16_bf16 v[48:63], v[162:165], v[166:169], v[48:63]
	s_waitcnt lgkmcnt(0)
	v_mfma_f32_32x32x16_bf16 v[32:47], v[162:165], v[174:177], v[32:47]
	v_mfma_f32_32x32x16_bf16 v[16:31], v[170:173], v[166:169], v[16:31]
	v_mfma_f32_32x32x16_bf16 v[0:15], v[170:173], v[174:177], v[0:15]
	ds_read_b128 v[162:165], v90
	ds_read_b128 v[166:169], v91 offset:32768
	ds_read_b128 v[170:173], v90 offset:4096
	ds_read_b128 v[174:177], v91 offset:36864
	s_waitcnt lgkmcnt(2)
	v_mfma_f32_32x32x16_bf16 v[48:63], v[162:165], v[166:169], v[48:63]
	s_waitcnt lgkmcnt(0)
	v_mfma_f32_32x32x16_bf16 v[32:47], v[162:165], v[174:177], v[32:47]
	v_mfma_f32_32x32x16_bf16 v[16:31], v[170:173], v[166:169], v[16:31]
	v_mfma_f32_32x32x16_bf16 v[0:15], v[170:173], v[174:177], v[0:15]
	ds_read_b128 v[162:165], v88
	ds_read_b128 v[166:169], v89 offset:32768
	ds_read_b128 v[170:173], v88 offset:4096
	ds_read_b128 v[174:177], v89 offset:36864
	s_waitcnt lgkmcnt(2)
	v_mfma_f32_32x32x16_bf16 v[48:63], v[162:165], v[166:169], v[48:63]
	s_waitcnt lgkmcnt(0)
	v_mfma_f32_32x32x16_bf16 v[32:47], v[162:165], v[174:177], v[32:47]
	v_mfma_f32_32x32x16_bf16 v[16:31], v[170:173], v[166:169], v[16:31]
	v_mfma_f32_32x32x16_bf16 v[0:15], v[170:173], v[174:177], v[0:15]
	ds_read_b128 v[162:165], v86
	ds_read_b128 v[166:169], v87 offset:32768
	ds_read_b128 v[170:173], v86 offset:4096
	ds_read_b128 v[174:177], v87 offset:36864
	s_waitcnt vmcnt(13)
	ds_write_b128 v85, v[102:105] offset:16384
	ds_write_b128 v85, v[94:97] offset:20480
	ds_write_b128 v85, v[98:101] offset:24576
	s_waitcnt vmcnt(11)
	ds_write_b128 v85, v[110:113] offset:28672
	ds_write_b128 v85, v[106:109] offset:49152
	s_waitcnt vmcnt(10)
	ds_write_b128 v85, v[114:117] offset:53248
	s_waitcnt vmcnt(9)
	ds_write_b128 v85, v[118:121] offset:57344
	s_waitcnt vmcnt(8)
	ds_write_b128 v85, v[122:125] offset:61440
	s_waitcnt lgkmcnt(0)
	s_barrier
	global_load_dwordx4 v[94:97], v[70:71], off offset:1920
	s_nop 0
	global_load_dwordx4 v[70:73], v[72:73], off offset:1920
	s_nop 0
	global_load_dwordx4 v[98:101], v[66:67], off offset:1920
	s_nop 0
	global_load_dwordx4 v[66:69], v[68:69], off offset:1920
	s_nop 0
	global_load_dwordx4 v[102:105], v[74:75], off offset:1920
	s_nop 0
	global_load_dwordx4 v[74:77], v[76:77], off offset:1920
	s_nop 0
	global_load_dwordx4 v[106:109], v[78:79], off offset:1920
	s_nop 0
	global_load_dwordx4 v[78:81], v[80:81], off offset:1920
	v_mfma_f32_32x32x16_bf16 v[48:63], v[162:165], v[166:169], v[48:63]
	v_mfma_f32_32x32x16_bf16 v[32:47], v[162:165], v[174:177], v[32:47]
	v_mfma_f32_32x32x16_bf16 v[16:31], v[170:173], v[166:169], v[16:31]
	v_mfma_f32_32x32x16_bf16 v[0:15], v[170:173], v[174:177], v[0:15]
	ds_read_b128 v[110:113], v92 offset:16384
	ds_read_b128 v[114:117], v93 offset:49152
	ds_read_b128 v[118:121], v93 offset:53248
	s_waitcnt lgkmcnt(1)
	v_mfma_f32_32x32x16_bf16 v[48:63], v[110:113], v[114:117], v[48:63]
	s_waitcnt lgkmcnt(0)
	v_mfma_f32_32x32x16_bf16 v[32:47], v[110:113], v[118:121], v[32:47]
	ds_read_b128 v[110:113], v92 offset:20480
	s_waitcnt lgkmcnt(0)
	v_mfma_f32_32x32x16_bf16 v[16:31], v[110:113], v[114:117], v[16:31]
	v_mfma_f32_32x32x16_bf16 v[0:15], v[110:113], v[118:121], v[0:15]
	ds_read_b128 v[110:113], v90 offset:16384
	ds_read_b128 v[114:117], v91 offset:49152
	ds_read_b128 v[118:121], v91 offset:53248
	s_waitcnt lgkmcnt(1)
	v_mfma_f32_32x32x16_bf16 v[48:63], v[110:113], v[114:117], v[48:63]
	s_waitcnt lgkmcnt(0)
	v_mfma_f32_32x32x16_bf16 v[32:47], v[110:113], v[118:121], v[32:47]
	ds_read_b128 v[110:113], v90 offset:20480
	s_waitcnt lgkmcnt(0)
	v_mfma_f32_32x32x16_bf16 v[16:31], v[110:113], v[114:117], v[16:31]
	v_mfma_f32_32x32x16_bf16 v[0:15], v[110:113], v[118:121], v[0:15]
	ds_read_b128 v[110:113], v88 offset:16384
	ds_read_b128 v[114:117], v89 offset:49152
	ds_read_b128 v[118:121], v89 offset:53248
	s_waitcnt lgkmcnt(1)
	v_mfma_f32_32x32x16_bf16 v[48:63], v[110:113], v[114:117], v[48:63]
	s_waitcnt lgkmcnt(0)
	v_mfma_f32_32x32x16_bf16 v[32:47], v[110:113], v[118:121], v[32:47]
	ds_read_b128 v[110:113], v88 offset:20480
	s_waitcnt lgkmcnt(0)
	v_mfma_f32_32x32x16_bf16 v[16:31], v[110:113], v[114:117], v[16:31]
	v_mfma_f32_32x32x16_bf16 v[0:15], v[110:113], v[118:121], v[0:15]
	ds_read_b128 v[110:113], v86 offset:16384
	ds_read_b128 v[114:117], v87 offset:49152
	ds_read_b128 v[118:121], v87 offset:53248
	s_waitcnt lgkmcnt(1)
	v_mfma_f32_32x32x16_bf16 v[48:63], v[110:113], v[114:117], v[48:63]
	s_waitcnt lgkmcnt(0)
	v_mfma_f32_32x32x16_bf16 v[32:47], v[110:113], v[118:121], v[32:47]
	ds_read_b128 v[110:113], v86 offset:20480
	s_waitcnt vmcnt(13)
	ds_write_b128 v85, v[136:139]
	ds_write_b128 v85, v[126:129] offset:4096
	ds_write_b128 v85, v[130:133] offset:8192
	s_waitcnt vmcnt(11)
	ds_write_b128 v85, v[144:147] offset:12288
	ds_write_b128 v85, v[140:143] offset:32768
	s_waitcnt vmcnt(10)
	ds_write_b128 v85, v[150:153] offset:36864
	s_waitcnt vmcnt(9)
	ds_write_b128 v85, v[154:157] offset:40960
	s_waitcnt vmcnt(8)
	ds_write_b128 v85, v[158:161] offset:45056
	s_waitcnt lgkmcnt(0)
	s_barrier
	v_mfma_f32_32x32x16_bf16 v[16:31], v[110:113], v[114:117], v[16:31]
	v_mfma_f32_32x32x16_bf16 v[0:15], v[110:113], v[118:121], v[0:15]
	ds_read_b128 v[110:113], v92
	ds_read_b128 v[114:117], v93 offset:32768
	ds_read_b128 v[118:121], v93 offset:36864
	s_waitcnt lgkmcnt(1)
	v_mfma_f32_32x32x16_bf16 v[48:63], v[110:113], v[114:117], v[48:63]
	s_waitcnt lgkmcnt(0)
	v_mfma_f32_32x32x16_bf16 v[32:47], v[110:113], v[118:121], v[32:47]
	ds_read_b128 v[110:113], v92 offset:4096
	s_waitcnt lgkmcnt(0)
	v_mfma_f32_32x32x16_bf16 v[16:31], v[110:113], v[114:117], v[16:31]
	v_mfma_f32_32x32x16_bf16 v[0:15], v[110:113], v[118:121], v[0:15]
	ds_read_b128 v[110:113], v90
	ds_read_b128 v[114:117], v91 offset:32768
	ds_read_b128 v[118:121], v91 offset:36864
	s_waitcnt lgkmcnt(1)
	v_mfma_f32_32x32x16_bf16 v[48:63], v[110:113], v[114:117], v[48:63]
	s_waitcnt lgkmcnt(0)
	v_mfma_f32_32x32x16_bf16 v[32:47], v[110:113], v[118:121], v[32:47]
	ds_read_b128 v[110:113], v90 offset:4096
	s_waitcnt lgkmcnt(0)
	v_mfma_f32_32x32x16_bf16 v[16:31], v[110:113], v[114:117], v[16:31]
	v_mfma_f32_32x32x16_bf16 v[0:15], v[110:113], v[118:121], v[0:15]
	ds_read_b128 v[110:113], v88
	ds_read_b128 v[114:117], v89 offset:32768
	ds_read_b128 v[118:121], v89 offset:36864
	s_waitcnt lgkmcnt(1)
	v_mfma_f32_32x32x16_bf16 v[48:63], v[110:113], v[114:117], v[48:63]
	s_waitcnt lgkmcnt(0)
	v_mfma_f32_32x32x16_bf16 v[32:47], v[110:113], v[118:121], v[32:47]
	ds_read_b128 v[110:113], v88 offset:4096
	s_waitcnt lgkmcnt(0)
	v_mfma_f32_32x32x16_bf16 v[16:31], v[110:113], v[114:117], v[16:31]
	v_mfma_f32_32x32x16_bf16 v[0:15], v[110:113], v[118:121], v[0:15]
	ds_read_b128 v[110:113], v86
	ds_read_b128 v[114:117], v87 offset:32768
	ds_read_b128 v[118:121], v87 offset:36864
	s_waitcnt lgkmcnt(1)
	v_mfma_f32_32x32x16_bf16 v[48:63], v[110:113], v[114:117], v[48:63]
	s_waitcnt lgkmcnt(0)
	v_mfma_f32_32x32x16_bf16 v[32:47], v[110:113], v[118:121], v[32:47]
	ds_read_b128 v[110:113], v86 offset:4096
	s_waitcnt vmcnt(5)
	ds_write_b128 v85, v[98:101] offset:16384
	ds_write_b128 v85, v[94:97] offset:20480
	ds_write_b128 v85, v[70:73] offset:24576
	s_waitcnt vmcnt(3)
	ds_write_b128 v85, v[102:105] offset:28672
	ds_write_b128 v85, v[66:69] offset:49152
	s_waitcnt vmcnt(2)
	ds_write_b128 v85, v[74:77] offset:53248
	s_waitcnt vmcnt(1)
	ds_write_b128 v85, v[106:109] offset:57344
	s_waitcnt vmcnt(0)
	ds_write_b128 v85, v[78:81] offset:61440
	s_waitcnt lgkmcnt(0)
	s_barrier
	v_mfma_f32_32x32x16_bf16 v[16:31], v[110:113], v[114:117], v[16:31]
	v_mfma_f32_32x32x16_bf16 v[0:15], v[110:113], v[118:121], v[0:15]
	ds_read_b128 v[66:69], v92 offset:16384
	ds_read_b128 v[70:73], v93 offset:49152
	ds_read_b128 v[74:77], v93 offset:53248
	v_add_u32_e32 v64, s0, v64
	v_lshl_or_b32 v64, v84, 2, v64
	v_cmp_lt_i32_e64 s[26:27], s33, v64
	s_waitcnt lgkmcnt(1)
	v_mfma_f32_32x32x16_bf16 v[48:63], v[66:69], v[70:73], v[48:63]
	s_waitcnt lgkmcnt(0)
	v_mfma_f32_32x32x16_bf16 v[32:47], v[66:69], v[74:77], v[32:47]
	ds_read_b128 v[66:69], v92 offset:20480
	s_waitcnt lgkmcnt(0)
	v_mfma_f32_32x32x16_bf16 v[16:31], v[66:69], v[70:73], v[16:31]
	v_mfma_f32_32x32x16_bf16 v[0:15], v[66:69], v[74:77], v[0:15]
	ds_read_b128 v[66:69], v90 offset:16384
	ds_read_b128 v[70:73], v91 offset:49152
	ds_read_b128 v[74:77], v91 offset:53248
	s_waitcnt lgkmcnt(1)
	v_mfma_f32_32x32x16_bf16 v[48:63], v[66:69], v[70:73], v[48:63]
	s_waitcnt lgkmcnt(0)
	v_mfma_f32_32x32x16_bf16 v[32:47], v[66:69], v[74:77], v[32:47]
	ds_read_b128 v[66:69], v90 offset:20480
	s_waitcnt lgkmcnt(0)
	v_mfma_f32_32x32x16_bf16 v[16:31], v[66:69], v[70:73], v[16:31]
	v_mfma_f32_32x32x16_bf16 v[0:15], v[66:69], v[74:77], v[0:15]
	ds_read_b128 v[66:69], v88 offset:16384
	ds_read_b128 v[70:73], v89 offset:49152
	ds_read_b128 v[74:77], v89 offset:53248
	s_waitcnt lgkmcnt(1)
	v_mfma_f32_32x32x16_bf16 v[48:63], v[66:69], v[70:73], v[48:63]
	s_waitcnt lgkmcnt(0)
	v_mfma_f32_32x32x16_bf16 v[32:47], v[66:69], v[74:77], v[32:47]
	ds_read_b128 v[66:69], v88 offset:20480
	s_waitcnt lgkmcnt(0)
	v_mfma_f32_32x32x16_bf16 v[16:31], v[66:69], v[70:73], v[16:31]
	v_mfma_f32_32x32x16_bf16 v[0:15], v[66:69], v[74:77], v[0:15]
	ds_read_b128 v[66:69], v86 offset:16384
	ds_read_b128 v[70:73], v87 offset:49152
	ds_read_b128 v[74:77], v87 offset:53248
	ds_read_b128 v[78:81], v86 offset:20480
	s_waitcnt lgkmcnt(0)
	s_barrier
	v_mfma_f32_32x32x16_bf16 v[48:63], v[66:69], v[70:73], v[48:63]
	v_mfma_f32_32x32x16_bf16 v[32:47], v[66:69], v[74:77], v[32:47]
	v_mfma_f32_32x32x16_bf16 v[16:31], v[78:81], v[70:73], v[16:31]
	v_mfma_f32_32x32x16_bf16 v[0:15], v[78:81], v[74:77], v[0:15]
	v_lshrrev_b32_e32 v92, 6, v218
	v_and_b32_e32 v90, 31, v218
	v_readfirstlane_b32 s2, v92
	v_lshlrev_b32_e32 v90, 2, v90
	v_bfe_u32 v91, v218, 5, 1
	v_readlane_b32 s38, v252, 27
	v_readlane_b32 s39, v252, 28
	v_readlane_b32 s36, v250, 3
	v_readlane_b32 s37, v250, 4
	v_lshl_or_b32 v82, v91, 14, v90
	v_add_u32_e32 v83, 0x1000, v82
	v_add_u32_e32 v84, 0x2000, v82
	v_add_u32_e32 v85, 0x3000, v82
	v_add_u32_e32 v86, 0x8000, v82
	v_add_u32_e32 v87, 0x9000, v82
	v_add_u32_e32 v88, 0xa000, v82
	v_add_u32_e32 v89, 0xb000, v82
	s_lshr_b32 s3, s2, 1
	s_and_b32 s2, s2, 1
	s_lshl_b32 s3, s3, 6
	s_lshl_b32 s2, s2, 6
	s_add_i32 s5, s0, s3
	s_add_i32 s6, s4, s2
	s_lshl_b32 s6, s6, 2
	s_sub_i32 s7, 0x40a0, s5
	s_ashr_i32 s7, s7, 4
	s_max_i32 s7, s7, 0
	s_min_i32 s7, s7, 4
	s_add_i32 s24, s5, 0
	s_cmp_ge_u32 s24, 0x2010
	s_cselect_b32 s25, 32, 16
	s_cselect_b32 s26, 0x10000, 0
	s_cselect_b32 s27, 0x2010, 0
	s_sub_i32 s28, s24, s25
	s_lshl_b32 s28, s28, 12
	s_sub_i32 s27, s24, s27
	s_add_u32 s8, s60, s28
	s_addc_u32 s9, s61, 0
	s_add_u32 s10, s38, s28
	s_addc_u32 s11, s39, 0
	s_cmp_lg_u32 s27, 0
	s_cbranch_scc1 .Lepi3_nm0
	s_mov_b64 s[8:9], s[74:75]
	s_add_u32 s10, s36, s26
	s_addc_u32 s11, s37, 0

.Lepi3_dn0:
	s_add_u32 s8, s8, s6
	s_addc_u32 s9, s9, 0
	s_add_u32 s10, s10, s6
	s_addc_u32 s11, s11, 0
	s_add_i32 s24, s5, 16
	s_cmp_ge_u32 s24, 0x2010
	s_cselect_b32 s25, 32, 16
	s_cselect_b32 s26, 0x10000, 0
	s_cselect_b32 s27, 0x2010, 0
	s_sub_i32 s28, s24, s25
	s_lshl_b32 s28, s28, 12
	s_sub_i32 s27, s24, s27
	s_add_u32 s12, s60, s28
	s_addc_u32 s13, s61, 0
	s_add_u32 s14, s38, s28
	s_addc_u32 s15, s39, 0
	s_cmp_lg_u32 s27, 0
	s_cbranch_scc1 .Lepi3_nm1
	s_mov_b64 s[12:13], s[74:75]
	s_add_u32 s14, s36, s26
	s_addc_u32 s15, s37, 0

.Lepi3_dn1:
	s_add_u32 s12, s12, s6
	s_addc_u32 s13, s13, 0
	s_add_u32 s14, s14, s6
	s_addc_u32 s15, s15, 0
	s_add_i32 s24, s5, 32
	s_cmp_ge_u32 s24, 0x2010
	s_cselect_b32 s25, 32, 16
	s_cselect_b32 s26, 0x10000, 0
	s_cselect_b32 s27, 0x2010, 0
	s_sub_i32 s28, s24, s25
	s_lshl_b32 s28, s28, 12
	s_sub_i32 s27, s24, s27
	s_add_u32 s16, s60, s28
	s_addc_u32 s17, s61, 0
	s_add_u32 s18, s38, s28
	s_addc_u32 s19, s39, 0
	s_cmp_lg_u32 s27, 0
	s_cbranch_scc1 .Lepi3_nm2
	s_mov_b64 s[16:17], s[74:75]
	s_add_u32 s18, s36, s26
	s_addc_u32 s19, s37, 0

.Lepi3_dn2:
	s_add_u32 s16, s16, s6
	s_addc_u32 s17, s17, 0
	s_add_u32 s18, s18, s6
	s_addc_u32 s19, s19, 0
	s_add_i32 s24, s5, 48
	s_cmp_ge_u32 s24, 0x2010
	s_cselect_b32 s25, 32, 16
	s_cselect_b32 s26, 0x10000, 0
	s_cselect_b32 s27, 0x2010, 0
	s_sub_i32 s28, s24, s25
	s_lshl_b32 s28, s28, 12
	s_sub_i32 s27, s24, s27
	s_add_u32 s20, s60, s28
	s_addc_u32 s21, s61, 0
	s_add_u32 s22, s38, s28
	s_addc_u32 s23, s39, 0
	s_cmp_lg_u32 s27, 0
	s_cbranch_scc1 .Lepi3_nm3
	s_mov_b64 s[20:21], s[74:75]
	s_add_u32 s22, s36, s26
	s_addc_u32 s23, s37, 0

.Lepi3_dn3:
	s_add_u32 s20, s20, s6
	s_addc_u32 s21, s21, 0
	s_add_u32 s22, s22, s6
	s_addc_u32 s23, s23, 0
	global_load_dword v96, v82, s[10:11] nt
	global_load_dword v97, v82, s[10:11] offset:128 nt
	global_load_dword v98, v83, s[10:11] nt
	global_load_dword v99, v83, s[10:11] offset:128 nt
	global_load_dword v100, v84, s[10:11] nt
	global_load_dword v101, v84, s[10:11] offset:128 nt
	global_load_dword v102, v85, s[10:11] nt
	global_load_dword v103, v85, s[10:11] offset:128 nt
	global_load_dword v104, v86, s[10:11] nt
	global_load_dword v105, v86, s[10:11] offset:128 nt
	global_load_dword v106, v87, s[10:11] nt
	global_load_dword v107, v87, s[10:11] offset:128 nt
	global_load_dword v108, v88, s[10:11] nt
	global_load_dword v109, v88, s[10:11] offset:128 nt
	global_load_dword v110, v89, s[10:11] nt
	global_load_dword v111, v89, s[10:11] offset:128 nt
	global_load_dword v112, v82, s[14:15] nt
	global_load_dword v113, v82, s[14:15] offset:128 nt
	global_load_dword v114, v83, s[14:15] nt
	global_load_dword v115, v83, s[14:15] offset:128 nt
	global_load_dword v116, v84, s[14:15] nt
	global_load_dword v117, v84, s[14:15] offset:128 nt
	global_load_dword v118, v85, s[14:15] nt
	global_load_dword v119, v85, s[14:15] offset:128 nt
	global_load_dword v120, v86, s[14:15] nt
	global_load_dword v121, v86, s[14:15] offset:128 nt
	global_load_dword v122, v87, s[14:15] nt
	global_load_dword v123, v87, s[14:15] offset:128 nt
	global_load_dword v124, v88, s[14:15] nt
	global_load_dword v125, v88, s[14:15] offset:128 nt
	global_load_dword v126, v89, s[14:15] nt
	global_load_dword v127, v89, s[14:15] offset:128 nt
	global_load_dword v128, v82, s[18:19] nt
	global_load_dword v129, v82, s[18:19] offset:128 nt
	global_load_dword v130, v83, s[18:19] nt
	global_load_dword v131, v83, s[18:19] offset:128 nt
	global_load_dword v132, v84, s[18:19] nt
	global_load_dword v133, v84, s[18:19] offset:128 nt
	global_load_dword v136, v85, s[18:19] nt
	global_load_dword v137, v85, s[18:19] offset:128 nt
	global_load_dword v138, v86, s[18:19] nt
	global_load_dword v139, v86, s[18:19] offset:128 nt
	global_load_dword v140, v87, s[18:19] nt
	global_load_dword v141, v87, s[18:19] offset:128 nt
	global_load_dword v142, v88, s[18:19] nt
	global_load_dword v143, v88, s[18:19] offset:128 nt
	global_load_dword v144, v89, s[18:19] nt
	global_load_dword v145, v89, s[18:19] offset:128 nt
	global_load_dword v146, v82, s[22:23] nt
	global_load_dword v147, v82, s[22:23] offset:128 nt
	global_load_dword v148, v83, s[22:23] nt
	global_load_dword v150, v83, s[22:23] offset:128 nt
	global_load_dword v151, v84, s[22:23] nt
	global_load_dword v152, v84, s[22:23] offset:128 nt
	global_load_dword v153, v85, s[22:23] nt
	global_load_dword v154, v85, s[22:23] offset:128 nt
	global_load_dword v155, v86, s[22:23] nt
	global_load_dword v156, v86, s[22:23] offset:128 nt
	global_load_dword v157, v87, s[22:23] nt
	global_load_dword v158, v87, s[22:23] offset:128 nt
	global_load_dword v159, v88, s[22:23] nt
	global_load_dword v160, v88, s[22:23] offset:128 nt
	global_load_dword v161, v89, s[22:23] nt
	global_load_dword v162, v89, s[22:23] offset:128 nt
	s_cmp_lt_u32 s7, 1
	s_cbranch_scc1 .Lepi3_end
	s_waitcnt vmcnt(48)
	v_add_f32_e32 v96, v96, v48
	global_store_dword v82, v96, s[10:11]
	v_add_f32_e32 v97, v97, v32
	global_store_dword v82, v97, s[10:11] offset:128
	v_add_f32_e32 v98, v98, v49
	global_store_dword v83, v98, s[10:11]
	v_add_f32_e32 v99, v99, v33
	global_store_dword v83, v99, s[10:11] offset:128
	v_add_f32_e32 v100, v100, v50
	global_store_dword v84, v100, s[10:11]
	v_add_f32_e32 v101, v101, v34
	global_store_dword v84, v101, s[10:11] offset:128
	v_add_f32_e32 v102, v102, v51
	global_store_dword v85, v102, s[10:11]
	v_add_f32_e32 v103, v103, v35
	global_store_dword v85, v103, s[10:11] offset:128
	v_add_f32_e32 v104, v104, v52
	global_store_dword v86, v104, s[10:11]
	v_add_f32_e32 v105, v105, v36
	global_store_dword v86, v105, s[10:11] offset:128
	v_add_f32_e32 v106, v106, v53
	global_store_dword v87, v106, s[10:11]
	v_add_f32_e32 v107, v107, v37
	global_store_dword v87, v107, s[10:11] offset:128
	v_add_f32_e32 v108, v108, v54
	global_store_dword v88, v108, s[10:11]
	v_add_f32_e32 v109, v109, v38
	global_store_dword v88, v109, s[10:11] offset:128
	v_add_f32_e32 v110, v110, v55
	global_store_dword v89, v110, s[10:11]
	v_add_f32_e32 v111, v111, v39
	global_store_dword v89, v111, s[10:11] offset:128
	s_cmp_lt_u32 s7, 2
	s_cbranch_scc1 .Lepi3_end
	s_waitcnt vmcnt(48)
	v_add_f32_e32 v112, v112, v56
	global_store_dword v82, v112, s[14:15]
	v_add_f32_e32 v113, v113, v40
	global_store_dword v82, v113, s[14:15] offset:128
	v_add_f32_e32 v114, v114, v57
	global_store_dword v83, v114, s[14:15]
	v_add_f32_e32 v115, v115, v41
	global_store_dword v83, v115, s[14:15] offset:128
	v_add_f32_e32 v116, v116, v58
	global_store_dword v84, v116, s[14:15]
	v_add_f32_e32 v117, v117, v42
	global_store_dword v84, v117, s[14:15] offset:128
	v_add_f32_e32 v118, v118, v59
	global_store_dword v85, v118, s[14:15]
	v_add_f32_e32 v119, v119, v43
	global_store_dword v85, v119, s[14:15] offset:128
	v_add_f32_e32 v120, v120, v60
	global_store_dword v86, v120, s[14:15]
	v_add_f32_e32 v121, v121, v44
	global_store_dword v86, v121, s[14:15] offset:128
	v_add_f32_e32 v122, v122, v61
	global_store_dword v87, v122, s[14:15]
	v_add_f32_e32 v123, v123, v45
	global_store_dword v87, v123, s[14:15] offset:128
	v_add_f32_e32 v124, v124, v62
	global_store_dword v88, v124, s[14:15]
	v_add_f32_e32 v125, v125, v46
	global_store_dword v88, v125, s[14:15] offset:128
	v_add_f32_e32 v126, v126, v63
	global_store_dword v89, v126, s[14:15]
	v_add_f32_e32 v127, v127, v47
	global_store_dword v89, v127, s[14:15] offset:128
	s_cmp_lt_u32 s7, 3
	s_cbranch_scc1 .Lepi3_end
	s_waitcnt vmcnt(48)
	v_add_f32_e32 v128, v128, v16
	global_store_dword v82, v128, s[18:19]
	v_add_f32_e32 v129, v129, v0
	global_store_dword v82, v129, s[18:19] offset:128
	v_add_f32_e32 v130, v130, v17
	global_store_dword v83, v130, s[18:19]
	v_add_f32_e32 v131, v131, v1
	global_store_dword v83, v131, s[18:19] offset:128
	v_add_f32_e32 v132, v132, v18
	global_store_dword v84, v132, s[18:19]
	v_add_f32_e32 v133, v133, v2
	global_store_dword v84, v133, s[18:19] offset:128
	v_add_f32_e32 v136, v136, v19
	global_store_dword v85, v136, s[18:19]
	v_add_f32_e32 v137, v137, v3
	global_store_dword v85, v137, s[18:19] offset:128
	v_add_f32_e32 v138, v138, v20
	global_store_dword v86, v138, s[18:19]
	v_add_f32_e32 v139, v139, v4
	global_store_dword v86, v139, s[18:19] offset:128
	v_add_f32_e32 v140, v140, v21
	global_store_dword v87, v140, s[18:19]
	v_add_f32_e32 v141, v141, v5
	global_store_dword v87, v141, s[18:19] offset:128
	v_add_f32_e32 v142, v142, v22
	global_store_dword v88, v142, s[18:19]
	v_add_f32_e32 v143, v143, v6
	global_store_dword v88, v143, s[18:19] offset:128
	v_add_f32_e32 v144, v144, v23
	global_store_dword v89, v144, s[18:19]
	v_add_f32_e32 v145, v145, v7
	global_store_dword v89, v145, s[18:19] offset:128
	s_cmp_lt_u32 s7, 4
	s_cbranch_scc1 .Lepi3_end
	s_waitcnt vmcnt(48)
	v_add_f32_e32 v146, v146, v24
	global_store_dword v82, v146, s[22:23]
	v_add_f32_e32 v147, v147, v8
	global_store_dword v82, v147, s[22:23] offset:128
	v_add_f32_e32 v148, v148, v25
	global_store_dword v83, v148, s[22:23]
	v_add_f32_e32 v150, v150, v9
	global_store_dword v83, v150, s[22:23] offset:128
	v_add_f32_e32 v151, v151, v26
	global_store_dword v84, v151, s[22:23]
	v_add_f32_e32 v152, v152, v10
	global_store_dword v84, v152, s[22:23] offset:128
	v_add_f32_e32 v153, v153, v27
	global_store_dword v85, v153, s[22:23]
	v_add_f32_e32 v154, v154, v11
	global_store_dword v85, v154, s[22:23] offset:128
	v_add_f32_e32 v155, v155, v28
	global_store_dword v86, v155, s[22:23]
	v_add_f32_e32 v156, v156, v12
	global_store_dword v86, v156, s[22:23] offset:128
	v_add_f32_e32 v157, v157, v29
	global_store_dword v87, v157, s[22:23]
	v_add_f32_e32 v158, v158, v13
	global_store_dword v87, v158, s[22:23] offset:128
	v_add_f32_e32 v159, v159, v30
	global_store_dword v88, v159, s[22:23]
	v_add_f32_e32 v160, v160, v14
	global_store_dword v88, v160, s[22:23] offset:128
	v_add_f32_e32 v161, v161, v31
	global_store_dword v89, v161, s[22:23]
	v_add_f32_e32 v162, v162, v15
	global_store_dword v89, v162, s[22:23] offset:128
.Lepi3_end:
	s_branch .LBB0_2390
.LBB0_3031:
	s_waitcnt vmcnt(0)
	s_barrier
	s_mov_b64 s[2:3], exec
	v_readlane_b32 s0, v252, 33
	v_readlane_b32 s1, v252, 34
	s_and_b64 s[0:1], s[2:3], s[0:1]
	s_mov_b64 exec, s[0:1]
	s_cbranch_execz .LBB0_3043
	s_waitcnt vmcnt(3)
	v_mov_b32_e32 v0, 0x12400
	ds_read_b32 v0, v0
	s_mov_b64 s[0:1], -1
	s_waitcnt lgkmcnt(0)
	v_cmp_eq_u32_e32 vcc, 0, v0
	s_cbranch_vccz .LBB0_3042
	s_waitcnt vmcnt(2)
	v_mbcnt_hi_u32_b32 v5, -1, v219
	v_and_b32_e32 v0, 64, v5
	v_add_u32_e32 v6, 64, v0
	v_xor_b32_e32 v0, 32, v5
	v_cmp_lt_i32_e32 vcc, v0, v6
	v_xor_b32_e32 v1, 16, v5
	v_xor_b32_e32 v2, 8, v5
	v_cndmask_b32_e32 v0, v5, v0, vcc
	v_cmp_lt_i32_e32 vcc, v1, v6
	v_xor_b32_e32 v3, 4, v5
	v_xor_b32_e32 v4, 2, v5
	v_cndmask_b32_e32 v1, v5, v1, vcc
	v_cmp_lt_i32_e32 vcc, v2, v6
	v_xor_b32_e32 v7, 1, v5
	v_lshlrev_b32_e32 v0, 2, v0
	v_cndmask_b32_e32 v2, v5, v2, vcc
	v_cmp_lt_i32_e32 vcc, v3, v6
	v_lshlrev_b32_e32 v1, 2, v1
	v_lshlrev_b32_e32 v2, 2, v2
	v_cndmask_b32_e32 v3, v5, v3, vcc
	v_cmp_lt_i32_e32 vcc, v4, v6
	v_lshlrev_b32_e32 v3, 2, v3
	s_mov_b64 s[4:5], 0
	v_cndmask_b32_e32 v4, v5, v4, vcc
	v_cmp_lt_i32_e32 vcc, v7, v6
	v_lshlrev_b32_e32 v4, 2, v4
	v_mov_b32_e32 v6, 0x100000
	v_cndmask_b32_e32 v5, v5, v7, vcc
	v_lshlrev_b32_e32 v5, 2, v5
	s_branch .LBB0_3035
